# phase3_sample B operand staged by LDS-DMA (4 rows x 256 contiguous bytes per DMA, XOR-swizzled pieces), fragments read from LDS
# speedup vs baseline: 1.0313x; 1.0005x over previous
.LBB0_921:
	s_and_b32 s3, s5, 0x3c0
	v_or_b32_e32 v2, s3, v43
	v_lshlrev_b32_e32 v154, 11, v2
	s_and_b32 s2, s4, 0xffffffe0
	v_lshl_add_u64 v[60:61], v[38:39], 0, v[154:155]
	v_add_u32_e32 v40, s2, v42
	v_ashrrev_i32_e32 v41, 31, v40
	v_lshlrev_b64 v[62:63], 11, v[40:41]
	v_lshl_add_u64 v[64:65], v[36:37], 0, v[62:63]
	s_mov_b32 s2, 0x10000
	v_add_co_u32_e32 v66, vcc, s2, v60
	s_mov_b32 s2, 0x7060302
	s_nop 0
	v_addc_co_u32_e32 v67, vcc, 0, v61, vcc
	v_lshrrev_b32_e64 v64, 4, s6
	v_lshrrev_b32_e32 v65, 6, v0
	v_lshl_add_u32 v64, v64, 3, v65
	v_lshlrev_b32_e32 v64, 13, v64
	v_and_b32_e32 v65, 63, v0
	v_lshl_add_u32 v64, v65, 4, v64
	v_add_u32_e32 v64, 0x2001000, v64
	v_mov_b32_e32 v65, 0
	v_lshl_add_u64 v[64:65], s[62:63], 0, v[64:65]
	v_readfirstlane_b32 s98, v60
	v_readfirstlane_b32 s99, v61
	v_lshrrev_b32_e32 v216, 6, v0
	s_nop 1
	v_readfirstlane_b32 s100, v216
	s_lshl_b32 s100, s100, 14
	s_add_i32 s100, s100, 32
	v_bfe_u32 v216, v0, 4, 2
	v_and_b32_e32 v217, 15, v0
	v_add_u32_e32 v226, 0, v216
	v_xor_b32_e32 v226, v226, v217
	v_lshlrev_b32_e32 v226, 4, v226
	v_lshl_add_u32 v226, v216, 11, v226
	v_add_u32_e32 v227, 4, v216
	v_xor_b32_e32 v227, v227, v217
	v_lshlrev_b32_e32 v227, 4, v227
	v_lshl_add_u32 v227, v216, 11, v227
	v_add_u32_e32 v228, 8, v216
	v_xor_b32_e32 v228, v228, v217
	v_lshlrev_b32_e32 v228, 4, v228
	v_lshl_add_u32 v228, v216, 11, v228
	v_add_u32_e32 v229, 12, v216
	v_xor_b32_e32 v229, v229, v217
	v_lshlrev_b32_e32 v229, 4, v229
	v_lshl_add_u32 v229, v216, 11, v229
	s_add_i32 m0, s100, 0x0
	s_nop 0
	global_load_lds_dwordx4 v226, s[98:99]
	s_add_u32 s98, s98, 0x2000
	s_addc_u32 s99, s99, 0
	s_add_i32 m0, s100, 0x400
	s_nop 0
	global_load_lds_dwordx4 v227, s[98:99]
	s_add_u32 s98, s98, 0x2000
	s_addc_u32 s99, s99, 0
	s_add_i32 m0, s100, 0x800
	s_nop 0
	global_load_lds_dwordx4 v228, s[98:99]
	s_add_u32 s98, s98, 0x2000
	s_addc_u32 s99, s99, 0
	s_add_i32 m0, s100, 0xc00
	s_nop 0
	global_load_lds_dwordx4 v229, s[98:99]
	s_add_u32 s98, s98, 0x2000
	s_addc_u32 s99, s99, 0
	s_add_i32 m0, s100, 0x1000
	s_nop 0
	global_load_lds_dwordx4 v226, s[98:99]
	s_add_u32 s98, s98, 0x2000
	s_addc_u32 s99, s99, 0
	s_add_i32 m0, s100, 0x1400
	s_nop 0
	global_load_lds_dwordx4 v227, s[98:99]
	s_add_u32 s98, s98, 0x2000
	s_addc_u32 s99, s99, 0
	s_add_i32 m0, s100, 0x1800
	s_nop 0
	global_load_lds_dwordx4 v228, s[98:99]
	s_add_u32 s98, s98, 0x2000
	s_addc_u32 s99, s99, 0
	s_add_i32 m0, s100, 0x1c00
	s_nop 0
	global_load_lds_dwordx4 v229, s[98:99]
	s_add_u32 s98, s98, 0x2000
	s_addc_u32 s99, s99, 0
	s_add_i32 m0, s100, 0x2000
	s_nop 0
	global_load_lds_dwordx4 v226, s[98:99]
	s_add_u32 s98, s98, 0x2000
	s_addc_u32 s99, s99, 0
	s_add_i32 m0, s100, 0x2400
	s_nop 0
	global_load_lds_dwordx4 v227, s[98:99]
	s_add_u32 s98, s98, 0x2000
	s_addc_u32 s99, s99, 0
	s_add_i32 m0, s100, 0x2800
	s_nop 0
	global_load_lds_dwordx4 v228, s[98:99]
	s_add_u32 s98, s98, 0x2000
	s_addc_u32 s99, s99, 0
	s_add_i32 m0, s100, 0x2c00
	s_nop 0
	global_load_lds_dwordx4 v229, s[98:99]
	s_add_u32 s98, s98, 0x2000
	s_addc_u32 s99, s99, 0
	s_add_i32 m0, s100, 0x3000
	s_nop 0
	global_load_lds_dwordx4 v226, s[98:99]
	s_add_u32 s98, s98, 0x2000
	s_addc_u32 s99, s99, 0
	s_add_i32 m0, s100, 0x3400
	s_nop 0
	global_load_lds_dwordx4 v227, s[98:99]
	s_add_u32 s98, s98, 0x2000
	s_addc_u32 s99, s99, 0
	s_add_i32 m0, s100, 0x3800
	s_nop 0
	global_load_lds_dwordx4 v228, s[98:99]
	s_add_u32 s98, s98, 0x2000
	s_addc_u32 s99, s99, 0
	s_add_i32 m0, s100, 0x3c00
	s_nop 0
	global_load_lds_dwordx4 v229, s[98:99]
	global_load_dwordx4 v[100:103], v[64:65], off offset:-4096
	global_load_dwordx4 v[104:107], v[64:65], off offset:-3072
	global_load_dwordx4 v[108:111], v[64:65], off offset:-2048
	global_load_dwordx4 v[112:115], v[64:65], off offset:-1024
	global_load_dwordx4 v[116:119], v[64:65], off
	global_load_dwordx4 v[120:123], v[64:65], off offset:1024
	global_load_dwordx4 v[124:127], v[64:65], off offset:2048
	global_load_dwordx4 v[128:131], v[64:65], off offset:3072
	v_and_b32_e32 v216, 31, v0
	v_lshlrev_b32_e32 v216, 8, v216
	v_add_u32_e32 v216, s100, v216
	v_bfe_u32 v217, v0, 5, 1
	v_xor_b32_e32 v217, v217, v0
	v_and_b32_e32 v217, 1, v217
	v_lshl_add_u32 v216, v217, 4, v216
	v_and_b32_e32 v217, 14, v0
	v_lshlrev_b32_e32 v217, 4, v217
	v_xor_b32_e32 v218, 0x0, v217
	v_add_u32_e32 v218, v216, v218
	v_xor_b32_e32 v219, 0x20, v217
	v_add_u32_e32 v219, v216, v219
	v_xor_b32_e32 v220, 0x40, v217
	v_add_u32_e32 v220, v216, v220
	v_xor_b32_e32 v221, 0x60, v217
	v_add_u32_e32 v221, v216, v221
	v_xor_b32_e32 v222, 0x80, v217
	v_add_u32_e32 v222, v216, v222
	v_xor_b32_e32 v223, 0xa0, v217
	v_add_u32_e32 v223, v216, v223
	v_xor_b32_e32 v224, 0xc0, v217
	v_add_u32_e32 v224, v216, v224
	v_xor_b32_e32 v225, 0xe0, v217
	v_add_u32_e32 v225, v216, v225
	v_lshl_add_u64 v[60:61], s[58:59], 0, v[62:63]
	v_add_u32_e32 v56, s3, v44
	v_or_b32_e32 v58, v56, v34
	v_ashrrev_i32_e32 v59, 31, v58
	v_lshl_add_u64 v[58:59], v[58:59], 1, v[60:61]
	v_ashrrev_i32_e32 v57, 31, v56
	v_lshl_add_u64 v[216:217], v[56:57], 0, v[34:35]
	v_lshl_add_u64 v[216:217], v[216:217], 1, v[60:61]
	global_load_dword v214, v[58:59], off
	global_load_dword v215, v[216:217], off offset:64
	s_waitcnt vmcnt(10)
	s_barrier
	ds_read_b128 v[68:71], v218
	ds_read_b128 v[182:185], v218 offset:8192
	ds_read_b128 v[72:75], v219
	ds_read_b128 v[186:189], v219 offset:8192
	ds_read_b128 v[76:79], v220
	ds_read_b128 v[190:193], v220 offset:8192
	ds_read_b128 v[80:83], v221
	ds_read_b128 v[194:197], v221 offset:8192
	ds_read_b128 v[84:87], v222
	ds_read_b128 v[198:201], v222 offset:8192
	ds_read_b128 v[88:91], v223
	ds_read_b128 v[202:205], v223 offset:8192
	ds_read_b128 v[92:95], v224
	ds_read_b128 v[206:209], v224 offset:8192
	ds_read_b128 v[96:99], v225
	ds_read_b128 v[210:213], v225 offset:8192
	s_waitcnt lgkmcnt(0)
	s_barrier
	s_waitcnt vmcnt(9)
	v_mfma_f32_32x32x16_bf16 v[2:17], v[68:71], v[100:103], 0
	v_mfma_f32_32x32x16_bf16 v[18:33], v[182:185], v[100:103], 0
	s_waitcnt vmcnt(8)
	v_mfma_f32_32x32x16_bf16 v[2:17], v[72:75], v[104:107], v[2:17]
	v_mfma_f32_32x32x16_bf16 v[18:33], v[186:189], v[104:107], v[18:33]
	s_waitcnt vmcnt(7)
	v_mfma_f32_32x32x16_bf16 v[2:17], v[76:79], v[108:111], v[2:17]
	v_mfma_f32_32x32x16_bf16 v[18:33], v[190:193], v[108:111], v[18:33]
	s_waitcnt vmcnt(6)
	v_mfma_f32_32x32x16_bf16 v[2:17], v[80:83], v[112:115], v[2:17]
	v_mfma_f32_32x32x16_bf16 v[18:33], v[194:197], v[112:115], v[18:33]
	s_waitcnt vmcnt(5)
	v_mfma_f32_32x32x16_bf16 v[2:17], v[84:87], v[116:119], v[2:17]
	v_mfma_f32_32x32x16_bf16 v[18:33], v[198:201], v[116:119], v[18:33]
	s_waitcnt vmcnt(4)
	v_mfma_f32_32x32x16_bf16 v[2:17], v[88:91], v[120:123], v[2:17]
	v_mfma_f32_32x32x16_bf16 v[18:33], v[202:205], v[120:123], v[18:33]
	s_waitcnt vmcnt(3)
	v_mfma_f32_32x32x16_bf16 v[2:17], v[92:95], v[124:127], v[2:17]
	v_mfma_f32_32x32x16_bf16 v[18:33], v[206:209], v[124:127], v[18:33]
	s_waitcnt vmcnt(2)
	v_mfma_f32_32x32x16_bf16 v[2:17], v[96:99], v[128:131], v[2:17]
	v_mfma_f32_32x32x16_bf16 v[18:33], v[210:213], v[128:131], v[18:33]
	s_nop 7
	s_nop 4
	ds_write2st64_b32 v46, v2, v3 offset1:1
	ds_write2st64_b32 v46, v4, v5 offset0:2 offset1:3
	ds_write2st64_b32 v46, v6, v7 offset0:4 offset1:5
	ds_write2st64_b32 v46, v8, v9 offset0:6 offset1:7
	ds_write2st64_b32 v46, v10, v11 offset0:8 offset1:9
	ds_write2st64_b32 v46, v12, v13 offset0:10 offset1:11
	ds_write2st64_b32 v46, v14, v15 offset0:12 offset1:13
	ds_write2st64_b32 v46, v16, v17 offset0:14 offset1:15
	ds_write2st64_b32 v46, v18, v19 offset0:16 offset1:17
	ds_write2st64_b32 v46, v20, v21 offset0:18 offset1:19
	ds_write2st64_b32 v46, v22, v23 offset0:20 offset1:21
	ds_write2st64_b32 v46, v24, v25 offset0:22 offset1:23
	ds_write2st64_b32 v46, v26, v27 offset0:24 offset1:25
	ds_write2st64_b32 v46, v28, v29 offset0:26 offset1:27
	ds_write2st64_b32 v46, v30, v31 offset0:28 offset1:29
	ds_write2st64_b32 v46, v32, v33 offset0:30 offset1:31
	s_waitcnt lgkmcnt(0)
	s_barrier
	v_lshl_add_u64 v[2:3], v[56:57], 0, v[34:35]
	v_lshl_add_u64 v[4:5], v[2:3], 1, v[60:61]
	ds_read2st64_b32 v[2:3], v47 offset1:1
	ds_read2st64_b32 v[6:7], v47 offset0:32 offset1:33
	ds_read2st64_b32 v[8:9], v47 offset0:64 offset1:65
	ds_read2st64_b32 v[10:11], v47 offset0:96 offset1:97
	ds_read2st64_b32 v[12:13], v47 offset0:128 offset1:129
	ds_read2st64_b32 v[14:15], v47 offset0:160 offset1:161
	ds_read2st64_b32 v[16:17], v47 offset0:192 offset1:193
	ds_read2st64_b32 v[18:19], v47 offset0:224 offset1:225
	s_waitcnt lgkmcnt(7)
	v_pk_add_f32 v[2:3], v[2:3], 0 op_sel_hi:[1,0]
	s_waitcnt lgkmcnt(6)
	v_pk_add_f32 v[2:3], v[2:3], v[6:7]
	s_waitcnt vmcnt(0)
	v_and_b32_e32 v7, 0xffff0000, v214
	s_waitcnt lgkmcnt(5)
	v_pk_add_f32 v[2:3], v[2:3], v[8:9]
	v_lshlrev_b32_e32 v6, 16, v214
	s_waitcnt lgkmcnt(4)
	v_pk_add_f32 v[2:3], v[2:3], v[10:11]
	s_waitcnt lgkmcnt(3)
	v_pk_add_f32 v[2:3], v[2:3], v[12:13]
	s_waitcnt lgkmcnt(2)
	v_pk_add_f32 v[2:3], v[2:3], v[14:15]
	s_waitcnt lgkmcnt(1)
	v_pk_add_f32 v[2:3], v[2:3], v[16:17]
	s_waitcnt lgkmcnt(0)
	v_pk_add_f32 v[2:3], v[2:3], v[18:19]
	s_nop 0
	v_pk_add_f32 v[2:3], v[2:3], v[6:7]
	s_nop 0
	v_and_b32_sdwa v6, v3, v180 dst_sel:DWORD dst_unused:UNUSED_PAD src0_sel:WORD_1 src1_sel:DWORD
	v_and_b32_sdwa v7, v2, v180 dst_sel:DWORD dst_unused:UNUSED_PAD src0_sel:WORD_1 src1_sel:DWORD
	v_add3_u32 v7, v2, v7, s15
	v_add3_u32 v6, v3, v6, s15
	v_perm_b32 v6, v6, v7, s2
	global_store_dword v[58:59], v6, off sc1
	ds_read2st64_b32 v[6:7], v47 offset0:48 offset1:49
	ds_read2st64_b32 v[8:9], v47 offset0:16 offset1:17
	ds_read2st64_b32 v[10:11], v47 offset0:112 offset1:113
	ds_read2st64_b32 v[12:13], v47 offset0:80 offset1:81
	ds_read2st64_b32 v[14:15], v47 offset0:176 offset1:177
	ds_read2st64_b32 v[16:17], v47 offset0:144 offset1:145
	ds_read2st64_b32 v[18:19], v47 offset0:240 offset1:241
	ds_read2st64_b32 v[20:21], v47 offset0:208 offset1:209
	s_waitcnt lgkmcnt(6)
	v_pk_add_f32 v[8:9], v[8:9], 0 op_sel_hi:[1,0]
	v_pk_mul_f32 v[2:3], v[2:3], v[2:3]
	v_pk_add_f32 v[6:7], v[8:9], v[6:7]
	v_add_f32_e32 v8, v2, v3
	s_waitcnt lgkmcnt(4)
	v_pk_add_f32 v[6:7], v[6:7], v[12:13]
	v_and_b32_e32 v3, 0xffff0000, v215
	v_pk_add_f32 v[6:7], v[6:7], v[10:11]
	v_lshlrev_b32_e32 v2, 16, v215
	s_waitcnt lgkmcnt(2)
	v_pk_add_f32 v[6:7], v[6:7], v[16:17]
	s_nop 0
	v_pk_add_f32 v[6:7], v[6:7], v[14:15]
	s_waitcnt lgkmcnt(0)
	v_pk_add_f32 v[6:7], v[6:7], v[20:21]
	s_nop 0
	v_pk_add_f32 v[6:7], v[6:7], v[18:19]
	s_nop 0
	v_pk_add_f32 v[6:7], v[6:7], v[2:3]
	s_nop 0
	v_pk_mul_f32 v[2:3], v[6:7], v[6:7]
	v_and_b32_sdwa v9, v7, v180 dst_sel:DWORD dst_unused:UNUSED_PAD src0_sel:WORD_1 src1_sel:DWORD
	v_add_f32_e32 v2, v8, v2
	v_add_f32_e32 v2, v2, v3
	ds_bpermute_b32 v3, v45, v2
	v_and_b32_sdwa v8, v6, v180 dst_sel:DWORD dst_unused:UNUSED_PAD src0_sel:WORD_1 src1_sel:DWORD
	v_add3_u32 v6, v6, v8, s15
	v_add3_u32 v7, v7, v9, s15
	v_perm_b32 v6, v7, v6, s2
	global_store_dword v[4:5], v6, off offset:64 sc1
	s_and_saveexec_b64 s[2:3], s[40:41]
	s_cbranch_execz .LBB0_920
	v_lshl_add_u64 v[4:5], v[40:41], 2, s[0:1]
	s_waitcnt lgkmcnt(0)
	v_add_f32_e32 v2, v2, v3
	global_atomic_add_f32 v[4:5], v2, off
	s_branch .LBB0_920

.LBB0_959:
	s_and_b32 s3, s5, 0x3c0
	v_or_b32_e32 v2, s3, v43
	v_lshlrev_b32_e32 v154, 11, v2
	s_and_b32 s2, s4, 0xffffffe0
	v_lshl_add_u64 v[60:61], v[38:39], 0, v[154:155]
	v_add_u32_e32 v40, s2, v42
	v_ashrrev_i32_e32 v41, 31, v40
	v_lshlrev_b64 v[62:63], 11, v[40:41]
	v_lshl_add_u64 v[64:65], v[36:37], 0, v[62:63]
	s_mov_b32 s2, 0x10000
	v_add_co_u32_e32 v66, vcc, s2, v60
	s_mov_b32 s2, 0x7060302
	s_nop 0
	v_addc_co_u32_e32 v67, vcc, 0, v61, vcc
	v_lshrrev_b32_e64 v64, 4, s6
	v_lshrrev_b32_e32 v65, 6, v0
	v_lshl_add_u32 v64, v64, 3, v65
	v_lshlrev_b32_e32 v64, 13, v64
	v_and_b32_e32 v65, 63, v0
	v_lshl_add_u32 v64, v65, 4, v64
	v_add_u32_e32 v64, 0x2001000, v64
	v_mov_b32_e32 v65, 0
	v_lshl_add_u64 v[64:65], s[62:63], 0, v[64:65]
	v_readfirstlane_b32 s98, v60
	v_readfirstlane_b32 s99, v61
	v_lshrrev_b32_e32 v216, 6, v0
	s_nop 1
	v_readfirstlane_b32 s100, v216
	s_lshl_b32 s100, s100, 14
	s_add_i32 s100, s100, 32
	v_bfe_u32 v216, v0, 4, 2
	v_and_b32_e32 v217, 15, v0
	v_add_u32_e32 v226, 0, v216
	v_xor_b32_e32 v226, v226, v217
	v_lshlrev_b32_e32 v226, 4, v226
	v_lshl_add_u32 v226, v216, 11, v226
	v_add_u32_e32 v227, 4, v216
	v_xor_b32_e32 v227, v227, v217
	v_lshlrev_b32_e32 v227, 4, v227
	v_lshl_add_u32 v227, v216, 11, v227
	v_add_u32_e32 v228, 8, v216
	v_xor_b32_e32 v228, v228, v217
	v_lshlrev_b32_e32 v228, 4, v228
	v_lshl_add_u32 v228, v216, 11, v228
	v_add_u32_e32 v229, 12, v216
	v_xor_b32_e32 v229, v229, v217
	v_lshlrev_b32_e32 v229, 4, v229
	v_lshl_add_u32 v229, v216, 11, v229
	s_add_i32 m0, s100, 0x0
	s_nop 0
	global_load_lds_dwordx4 v226, s[98:99]
	s_add_u32 s98, s98, 0x2000
	s_addc_u32 s99, s99, 0
	s_add_i32 m0, s100, 0x400
	s_nop 0
	global_load_lds_dwordx4 v227, s[98:99]
	s_add_u32 s98, s98, 0x2000
	s_addc_u32 s99, s99, 0
	s_add_i32 m0, s100, 0x800
	s_nop 0
	global_load_lds_dwordx4 v228, s[98:99]
	s_add_u32 s98, s98, 0x2000
	s_addc_u32 s99, s99, 0
	s_add_i32 m0, s100, 0xc00
	s_nop 0
	global_load_lds_dwordx4 v229, s[98:99]
	s_add_u32 s98, s98, 0x2000
	s_addc_u32 s99, s99, 0
	s_add_i32 m0, s100, 0x1000
	s_nop 0
	global_load_lds_dwordx4 v226, s[98:99]
	s_add_u32 s98, s98, 0x2000
	s_addc_u32 s99, s99, 0
	s_add_i32 m0, s100, 0x1400
	s_nop 0
	global_load_lds_dwordx4 v227, s[98:99]
	s_add_u32 s98, s98, 0x2000
	s_addc_u32 s99, s99, 0
	s_add_i32 m0, s100, 0x1800
	s_nop 0
	global_load_lds_dwordx4 v228, s[98:99]
	s_add_u32 s98, s98, 0x2000
	s_addc_u32 s99, s99, 0
	s_add_i32 m0, s100, 0x1c00
	s_nop 0
	global_load_lds_dwordx4 v229, s[98:99]
	s_add_u32 s98, s98, 0x2000
	s_addc_u32 s99, s99, 0
	s_add_i32 m0, s100, 0x2000
	s_nop 0
	global_load_lds_dwordx4 v226, s[98:99]
	s_add_u32 s98, s98, 0x2000
	s_addc_u32 s99, s99, 0
	s_add_i32 m0, s100, 0x2400
	s_nop 0
	global_load_lds_dwordx4 v227, s[98:99]
	s_add_u32 s98, s98, 0x2000
	s_addc_u32 s99, s99, 0
	s_add_i32 m0, s100, 0x2800
	s_nop 0
	global_load_lds_dwordx4 v228, s[98:99]
	s_add_u32 s98, s98, 0x2000
	s_addc_u32 s99, s99, 0
	s_add_i32 m0, s100, 0x2c00
	s_nop 0
	global_load_lds_dwordx4 v229, s[98:99]
	s_add_u32 s98, s98, 0x2000
	s_addc_u32 s99, s99, 0
	s_add_i32 m0, s100, 0x3000
	s_nop 0
	global_load_lds_dwordx4 v226, s[98:99]
	s_add_u32 s98, s98, 0x2000
	s_addc_u32 s99, s99, 0
	s_add_i32 m0, s100, 0x3400
	s_nop 0
	global_load_lds_dwordx4 v227, s[98:99]
	s_add_u32 s98, s98, 0x2000
	s_addc_u32 s99, s99, 0
	s_add_i32 m0, s100, 0x3800
	s_nop 0
	global_load_lds_dwordx4 v228, s[98:99]
	s_add_u32 s98, s98, 0x2000
	s_addc_u32 s99, s99, 0
	s_add_i32 m0, s100, 0x3c00
	s_nop 0
	global_load_lds_dwordx4 v229, s[98:99]
	global_load_dwordx4 v[100:103], v[64:65], off offset:-4096
	global_load_dwordx4 v[104:107], v[64:65], off offset:-3072
	global_load_dwordx4 v[108:111], v[64:65], off offset:-2048
	global_load_dwordx4 v[112:115], v[64:65], off offset:-1024
	global_load_dwordx4 v[116:119], v[64:65], off
	global_load_dwordx4 v[120:123], v[64:65], off offset:1024
	global_load_dwordx4 v[124:127], v[64:65], off offset:2048
	global_load_dwordx4 v[128:131], v[64:65], off offset:3072
	v_and_b32_e32 v216, 31, v0
	v_lshlrev_b32_e32 v216, 8, v216
	v_add_u32_e32 v216, s100, v216
	v_bfe_u32 v217, v0, 5, 1
	v_xor_b32_e32 v217, v217, v0
	v_and_b32_e32 v217, 1, v217
	v_lshl_add_u32 v216, v217, 4, v216
	v_and_b32_e32 v217, 14, v0
	v_lshlrev_b32_e32 v217, 4, v217
	v_xor_b32_e32 v218, 0x0, v217
	v_add_u32_e32 v218, v216, v218
	v_xor_b32_e32 v219, 0x20, v217
	v_add_u32_e32 v219, v216, v219
	v_xor_b32_e32 v220, 0x40, v217
	v_add_u32_e32 v220, v216, v220
	v_xor_b32_e32 v221, 0x60, v217
	v_add_u32_e32 v221, v216, v221
	v_xor_b32_e32 v222, 0x80, v217
	v_add_u32_e32 v222, v216, v222
	v_xor_b32_e32 v223, 0xa0, v217
	v_add_u32_e32 v223, v216, v223
	v_xor_b32_e32 v224, 0xc0, v217
	v_add_u32_e32 v224, v216, v224
	v_xor_b32_e32 v225, 0xe0, v217
	v_add_u32_e32 v225, v216, v225
	v_lshl_add_u64 v[60:61], s[58:59], 0, v[62:63]
	v_add_u32_e32 v56, s3, v44
	v_or_b32_e32 v58, v56, v34
	v_ashrrev_i32_e32 v59, 31, v58
	v_lshl_add_u64 v[58:59], v[58:59], 1, v[60:61]
	v_ashrrev_i32_e32 v57, 31, v56
	v_lshl_add_u64 v[216:217], v[56:57], 0, v[34:35]
	v_lshl_add_u64 v[216:217], v[216:217], 1, v[60:61]
	global_load_dword v214, v[58:59], off
	global_load_dword v215, v[216:217], off offset:64
	s_waitcnt vmcnt(10)
	s_barrier
	ds_read_b128 v[68:71], v218
	ds_read_b128 v[182:185], v218 offset:8192
	ds_read_b128 v[72:75], v219
	ds_read_b128 v[186:189], v219 offset:8192
	ds_read_b128 v[76:79], v220
	ds_read_b128 v[190:193], v220 offset:8192
	ds_read_b128 v[80:83], v221
	ds_read_b128 v[194:197], v221 offset:8192
	ds_read_b128 v[84:87], v222
	ds_read_b128 v[198:201], v222 offset:8192
	ds_read_b128 v[88:91], v223
	ds_read_b128 v[202:205], v223 offset:8192
	ds_read_b128 v[92:95], v224
	ds_read_b128 v[206:209], v224 offset:8192
	ds_read_b128 v[96:99], v225
	ds_read_b128 v[210:213], v225 offset:8192
	s_waitcnt lgkmcnt(0)
	s_barrier
	s_waitcnt vmcnt(9)
	v_mfma_f32_32x32x16_bf16 v[2:17], v[68:71], v[100:103], 0
	v_mfma_f32_32x32x16_bf16 v[18:33], v[182:185], v[100:103], 0
	s_waitcnt vmcnt(8)
	v_mfma_f32_32x32x16_bf16 v[2:17], v[72:75], v[104:107], v[2:17]
	v_mfma_f32_32x32x16_bf16 v[18:33], v[186:189], v[104:107], v[18:33]
	s_waitcnt vmcnt(7)
	v_mfma_f32_32x32x16_bf16 v[2:17], v[76:79], v[108:111], v[2:17]
	v_mfma_f32_32x32x16_bf16 v[18:33], v[190:193], v[108:111], v[18:33]
	s_waitcnt vmcnt(6)
	v_mfma_f32_32x32x16_bf16 v[2:17], v[80:83], v[112:115], v[2:17]
	v_mfma_f32_32x32x16_bf16 v[18:33], v[194:197], v[112:115], v[18:33]
	s_waitcnt vmcnt(5)
	v_mfma_f32_32x32x16_bf16 v[2:17], v[84:87], v[116:119], v[2:17]
	v_mfma_f32_32x32x16_bf16 v[18:33], v[198:201], v[116:119], v[18:33]
	s_waitcnt vmcnt(4)
	v_mfma_f32_32x32x16_bf16 v[2:17], v[88:91], v[120:123], v[2:17]
	v_mfma_f32_32x32x16_bf16 v[18:33], v[202:205], v[120:123], v[18:33]
	s_waitcnt vmcnt(3)
	v_mfma_f32_32x32x16_bf16 v[2:17], v[92:95], v[124:127], v[2:17]
	v_mfma_f32_32x32x16_bf16 v[18:33], v[206:209], v[124:127], v[18:33]
	s_waitcnt vmcnt(2)
	v_mfma_f32_32x32x16_bf16 v[2:17], v[96:99], v[128:131], v[2:17]
	v_mfma_f32_32x32x16_bf16 v[18:33], v[210:213], v[128:131], v[18:33]
	s_nop 7
	s_nop 4
	ds_write2st64_b32 v46, v2, v3 offset1:1
	ds_write2st64_b32 v46, v4, v5 offset0:2 offset1:3
	ds_write2st64_b32 v46, v6, v7 offset0:4 offset1:5
	ds_write2st64_b32 v46, v8, v9 offset0:6 offset1:7
	ds_write2st64_b32 v46, v10, v11 offset0:8 offset1:9
	ds_write2st64_b32 v46, v12, v13 offset0:10 offset1:11
	ds_write2st64_b32 v46, v14, v15 offset0:12 offset1:13
	ds_write2st64_b32 v46, v16, v17 offset0:14 offset1:15
	ds_write2st64_b32 v46, v18, v19 offset0:16 offset1:17
	ds_write2st64_b32 v46, v20, v21 offset0:18 offset1:19
	ds_write2st64_b32 v46, v22, v23 offset0:20 offset1:21
	ds_write2st64_b32 v46, v24, v25 offset0:22 offset1:23
	ds_write2st64_b32 v46, v26, v27 offset0:24 offset1:25
	ds_write2st64_b32 v46, v28, v29 offset0:26 offset1:27
	ds_write2st64_b32 v46, v30, v31 offset0:28 offset1:29
	ds_write2st64_b32 v46, v32, v33 offset0:30 offset1:31
	s_waitcnt lgkmcnt(0)
	s_barrier
	v_lshl_add_u64 v[2:3], v[56:57], 0, v[34:35]
	v_lshl_add_u64 v[4:5], v[2:3], 1, v[60:61]
	ds_read2st64_b32 v[2:3], v47 offset1:1
	ds_read2st64_b32 v[6:7], v47 offset0:32 offset1:33
	ds_read2st64_b32 v[8:9], v47 offset0:64 offset1:65
	ds_read2st64_b32 v[10:11], v47 offset0:96 offset1:97
	ds_read2st64_b32 v[12:13], v47 offset0:128 offset1:129
	ds_read2st64_b32 v[14:15], v47 offset0:160 offset1:161
	ds_read2st64_b32 v[16:17], v47 offset0:192 offset1:193
	ds_read2st64_b32 v[18:19], v47 offset0:224 offset1:225
	s_waitcnt lgkmcnt(7)
	v_pk_add_f32 v[2:3], v[2:3], 0 op_sel_hi:[1,0]
	s_waitcnt lgkmcnt(6)
	v_pk_add_f32 v[2:3], v[2:3], v[6:7]
	s_waitcnt vmcnt(0)
	v_and_b32_e32 v7, 0xffff0000, v214
	s_waitcnt lgkmcnt(5)
	v_pk_add_f32 v[2:3], v[2:3], v[8:9]
	v_lshlrev_b32_e32 v6, 16, v214
	s_waitcnt lgkmcnt(4)
	v_pk_add_f32 v[2:3], v[2:3], v[10:11]
	s_waitcnt lgkmcnt(3)
	v_pk_add_f32 v[2:3], v[2:3], v[12:13]
	s_waitcnt lgkmcnt(2)
	v_pk_add_f32 v[2:3], v[2:3], v[14:15]
	s_waitcnt lgkmcnt(1)
	v_pk_add_f32 v[2:3], v[2:3], v[16:17]
	s_waitcnt lgkmcnt(0)
	v_pk_add_f32 v[2:3], v[2:3], v[18:19]
	s_nop 0
	v_pk_add_f32 v[2:3], v[2:3], v[6:7]
	s_nop 0
	v_and_b32_sdwa v6, v3, v180 dst_sel:DWORD dst_unused:UNUSED_PAD src0_sel:WORD_1 src1_sel:DWORD
	v_and_b32_sdwa v7, v2, v180 dst_sel:DWORD dst_unused:UNUSED_PAD src0_sel:WORD_1 src1_sel:DWORD
	v_add3_u32 v7, v2, v7, s15
	v_add3_u32 v6, v3, v6, s15
	v_perm_b32 v6, v6, v7, s2
	global_store_dword v[58:59], v6, off sc1
	ds_read2st64_b32 v[6:7], v47 offset0:48 offset1:49
	ds_read2st64_b32 v[8:9], v47 offset0:16 offset1:17
	ds_read2st64_b32 v[10:11], v47 offset0:112 offset1:113
	ds_read2st64_b32 v[12:13], v47 offset0:80 offset1:81
	ds_read2st64_b32 v[14:15], v47 offset0:176 offset1:177
	ds_read2st64_b32 v[16:17], v47 offset0:144 offset1:145
	ds_read2st64_b32 v[18:19], v47 offset0:240 offset1:241
	ds_read2st64_b32 v[20:21], v47 offset0:208 offset1:209
	s_waitcnt lgkmcnt(6)
	v_pk_add_f32 v[8:9], v[8:9], 0 op_sel_hi:[1,0]
	v_pk_mul_f32 v[2:3], v[2:3], v[2:3]
	v_pk_add_f32 v[6:7], v[8:9], v[6:7]
	v_add_f32_e32 v8, v2, v3
	s_waitcnt lgkmcnt(4)
	v_pk_add_f32 v[6:7], v[6:7], v[12:13]
	v_and_b32_e32 v3, 0xffff0000, v215
	v_pk_add_f32 v[6:7], v[6:7], v[10:11]
	v_lshlrev_b32_e32 v2, 16, v215
	s_waitcnt lgkmcnt(2)
	v_pk_add_f32 v[6:7], v[6:7], v[16:17]
	s_nop 0
	v_pk_add_f32 v[6:7], v[6:7], v[14:15]
	s_waitcnt lgkmcnt(0)
	v_pk_add_f32 v[6:7], v[6:7], v[20:21]
	s_nop 0
	v_pk_add_f32 v[6:7], v[6:7], v[18:19]
	s_nop 0
	v_pk_add_f32 v[6:7], v[6:7], v[2:3]
	s_nop 0
	v_pk_mul_f32 v[2:3], v[6:7], v[6:7]
	v_and_b32_sdwa v9, v7, v180 dst_sel:DWORD dst_unused:UNUSED_PAD src0_sel:WORD_1 src1_sel:DWORD
	v_add_f32_e32 v2, v8, v2
	v_add_f32_e32 v2, v2, v3
	ds_bpermute_b32 v3, v45, v2
	v_and_b32_sdwa v8, v6, v180 dst_sel:DWORD dst_unused:UNUSED_PAD src0_sel:WORD_1 src1_sel:DWORD
	v_add3_u32 v6, v6, v8, s15
	v_add3_u32 v7, v7, v9, s15
	v_perm_b32 v6, v7, v6, s2
	global_store_dword v[4:5], v6, off offset:64 sc1
	s_and_saveexec_b64 s[2:3], s[36:37]
	s_cbranch_execz .LBB0_958
	v_lshl_add_u64 v[4:5], v[40:41], 2, s[0:1]
	s_waitcnt lgkmcnt(0)
	v_add_f32_e32 v2, v2, v3
	global_atomic_add_f32 v[4:5], v2, off
	s_branch .LBB0_958
